# skip the stagger sleep on the 8 workgroups that carry a 5th GEMM unit in P7-out / P8; DMA prefetch distance 3
# speedup vs baseline: 1.0214x; 1.0054x over previous
.Ldma_sdone_2:
	v_lshrrev_b32_e32 v207, 2, v163
	v_lshrrev_b32_e32 v201, 3, v163
	v_xor_b32_e32 v207, v207, v201
	v_and_b32_e32 v207, 1, v207
	v_mul_u32_u24_e32 v207, 12, v207
	v_xor_b32_e32 v207, v163, v207
	v_mul_u32_u24_e32 v205, 0xd0, v207
	v_mul_u32_u24_e32 v206, 0x90, v163
	v_add_u32_e32 v206, 0x3400, v206
	v_add_u32_e32 v206, v206, v170
	s_mov_b32 m0, s60
	s_nop 0
	global_load_lds_dwordx4 v202, s[18:19]
	s_mov_b32 m0, s61
	s_nop 0
	global_load_lds_dwordx4 v203, s[18:19]
	s_mov_b32 m0, s66
	s_nop 0
	global_load_lds_dwordx4 v204, s[18:19]
	v_add_u32_e32 v202, v196, v202
	v_add_u32_e32 v203, v197, v203
	v_add_u32_e32 v204, v198, v204
	s_add_u32 m0, s60, 0x5800
	s_nop 0
	global_load_lds_dwordx4 v202, s[18:19]
	s_add_u32 m0, s61, 0x5800
	s_nop 0
	global_load_lds_dwordx4 v203, s[18:19]
	s_add_u32 m0, s66, 0x5800
	s_nop 0
	global_load_lds_dwordx4 v204, s[18:19]
	v_add_u32_e32 v202, v196, v202
	v_add_u32_e32 v203, v197, v203
	v_add_u32_e32 v204, v198, v204
	s_add_u32 m0, s60, 0xb000
	s_nop 0
	global_load_lds_dwordx4 v202, s[18:19]
	s_add_u32 m0, s61, 0xb000
	s_nop 0
	global_load_lds_dwordx4 v203, s[18:19]
	s_add_u32 m0, s66, 0xb000
	s_nop 0
	global_load_lds_dwordx4 v204, s[18:19]
	v_add_u32_e32 v202, v196, v202
	v_add_u32_e32 v203, v197, v203
	v_add_u32_e32 v204, v198, v204
	s_mov_b32 s13, 0
	s_waitcnt vmcnt(6)
	s_barrier
	s_branch .Ldma_top
.Ldma_top:
	s_add_u32 m0, s60, 0x10800
	s_nop 0
	global_load_lds_dwordx4 v202, s[18:19]
	s_add_u32 m0, s61, 0x10800
	s_nop 0
	global_load_lds_dwordx4 v203, s[18:19]
	s_add_u32 m0, s66, 0x10800
	s_nop 0
	global_load_lds_dwordx4 v204, s[18:19]
	s_add_i32 s44, s13, 4
	s_cmp_lt_u32 s44, s7
	s_cbranch_scc0 .Ldma_noadv_0
	v_add_u32_e32 v202, v196, v202
	v_add_u32_e32 v203, v197, v203
	v_add_u32_e32 v204, v198, v204

.Ldma_skip_0:
	s_waitcnt vmcnt(6)
	s_barrier
	s_mov_b32 m0, s60
	s_nop 0
	global_load_lds_dwordx4 v202, s[18:19]
	s_mov_b32 m0, s61
	s_nop 0
	global_load_lds_dwordx4 v203, s[18:19]
	s_mov_b32 m0, s66
	s_nop 0
	global_load_lds_dwordx4 v204, s[18:19]
	s_add_i32 s44, s13, 5
	s_cmp_lt_u32 s44, s7
	s_cbranch_scc0 .Ldma_noadv_1
	v_add_u32_e32 v202, v196, v202
	v_add_u32_e32 v203, v197, v203
	v_add_u32_e32 v204, v198, v204

.Ldma_skip_1:
	s_waitcnt vmcnt(6)
	s_barrier
	s_add_u32 m0, s60, 0x5800
	s_nop 0
	global_load_lds_dwordx4 v202, s[18:19]
	s_add_u32 m0, s61, 0x5800
	s_nop 0
	global_load_lds_dwordx4 v203, s[18:19]
	s_add_u32 m0, s66, 0x5800
	s_nop 0
	global_load_lds_dwordx4 v204, s[18:19]
	s_add_i32 s44, s13, 6
	s_cmp_lt_u32 s44, s7
	s_cbranch_scc0 .Ldma_noadv_2
	v_add_u32_e32 v202, v196, v202
	v_add_u32_e32 v203, v197, v203
	v_add_u32_e32 v204, v198, v204

.Ldma_skip_2:
	s_waitcnt vmcnt(6)
	s_barrier
	s_add_u32 m0, s60, 0xb000
	s_nop 0
	global_load_lds_dwordx4 v202, s[18:19]
	s_add_u32 m0, s61, 0xb000
	s_nop 0
	global_load_lds_dwordx4 v203, s[18:19]
	s_add_u32 m0, s66, 0xb000
	s_nop 0
	global_load_lds_dwordx4 v204, s[18:19]
	s_add_i32 s44, s13, 7
	s_cmp_lt_u32 s44, s7
	s_cbranch_scc0 .Ldma_noadv_3
	v_add_u32_e32 v202, v196, v202
	v_add_u32_e32 v203, v197, v203
	v_add_u32_e32 v204, v198, v204

.Ldma_skip_3:
	s_waitcnt vmcnt(6)
	s_barrier
	s_add_i32 s13, s13, 4
	s_cmp_lt_u32 s13, s7
	s_cbranch_scc1 .Ldma_top
	s_waitcnt vmcnt(0)
	s_barrier
	s_branch .LBB0_966

.LBB0_1401:
	s_bitcmp1_b32 s62, 0
	s_cselect_b64 s[0:1], -1, 0
	s_and_b64 vcc, exec, s[0:1]
	s_cbranch_vccz .LBB0_1404
	s_cmp_lt_u32 s62, 8
	s_cbranch_scc1 .LBB0_1404
	s_mov_b32 s0, 4
	s_cmp_lt_i32 s0, 1
	s_cbranch_scc1 .LBB0_1404

.LBB0_1482:
	s_or_b64 exec, exec, s[36:37]
	s_waitcnt lgkmcnt(0)
	s_barrier
	s_bitcmp0_b32 s62, 0
	s_cbranch_scc1 .LBB0_1485
	s_cmp_lt_u32 s62, 8
	s_cbranch_scc1 .LBB0_1485
	s_mov_b32 s0, 4
	s_cmp_lt_i32 s0, 1
	s_cbranch_scc1 .LBB0_1485
